# split + remap + hand-off latency: first counter poll issued right behind the atomic, shorter poll sleep
# speedup vs baseline: 1.0055x; 1.0019x over previous
; __global__ void __launch_bounds__(NWAVES * 64, 2) fwd_mega(Args args) {
;     ...
;             asm volatile("s_waitcnt vmcnt(0)" ::: "memory");
;             __syncthreads();
;             if (threadIdx.x == 0) { __builtin_amdgcn_fence(__ATOMIC_ACQUIRE, "agent"); asm volatile("s_waitcnt vmcnt(0)" ::: "memory"); }
;             __syncthreads();
.LBB0_680:
	s_waitcnt vmcnt(0)
	s_barrier
	s_mov_b64 s[6:7], exec
	v_readlane_b32 s0, v253, 12
	v_readlane_b32 s1, v253, 13
	s_and_b64 s[0:1], s[6:7], s[0:1]
	s_mov_b64 exec, s[0:1]
	s_cbranch_execz .LBB0_682
	s_waitcnt vmcnt(0)
	v_readlane_b32 s98, v253, 2
	v_readlane_b32 s99, v253, 3
	s_lshl_b32 s100, s3, 8
	s_add_i32 s100, s100, 0xe000
	s_add_u32 s98, s98, s100
	s_addc_u32 s99, s99, 0
	v_mov_b32_e32 v251, 0
	v_mov_b32_e32 v252, 1
	global_atomic_add v251, v252, s[98:99]
	s_movk_i32 s100, 0x1000
.Lhsync_spin_7:
	global_load_dword v252, v251, s[98:99] sc1
	s_waitcnt vmcnt(0)
	v_readfirstlane_b32 s101, v252
	s_cmp_ge_u32 s101, 11
	s_cbranch_scc1 .Lhsync_done_7
	s_sleep 1
	s_sub_u32 s100, s100, 1
	s_cmp_lg_u32 s100, 0
	s_cbranch_scc1 .Lhsync_spin_7

; __global__ void __launch_bounds__(NWAVES * 64, 2) fwd_mega(Args args) {
;     ...
;             asm volatile("s_waitcnt vmcnt(0)" ::: "memory");
;             __syncthreads();
;             if (threadIdx.x == 0) { __builtin_amdgcn_fence(__ATOMIC_ACQUIRE, "agent"); asm volatile("s_waitcnt vmcnt(0)" ::: "memory"); }
;             __syncthreads();
.LBB0_1752:
	s_waitcnt vmcnt(0)
	s_barrier
	s_mov_b64 s[8:9], exec
	v_readlane_b32 s0, v253, 12
	v_readlane_b32 s1, v253, 13
	s_and_b64 s[0:1], s[8:9], s[0:1]
	s_mov_b64 exec, s[0:1]
	s_cbranch_execz .LBB0_1754
	s_waitcnt vmcnt(0)
	v_readlane_b32 s98, v253, 2
	v_readlane_b32 s99, v253, 3
	s_lshl_b32 s100, s7, 8
	s_add_i32 s100, s100, 0xf000
	s_add_u32 s98, s98, s100
	s_addc_u32 s99, s99, 0
	v_mov_b32_e32 v251, 0
	v_mov_b32_e32 v252, 1
	global_atomic_add v251, v252, s[98:99]
	s_movk_i32 s100, 0x1000
